# gla_a units rebalanced 14/18 between the workgroups that also run the S5 input GEMM and those that do not; 64-bit zeroing in the last two GEMM instances
# baseline (speedup 1.0000x reference)
; template <class Epi>
; __device__ __forceinline__ void gemm_phase(LAS unsigned char* lds, const Gemm g, const Epi& E) {
;     ...
;         const char* nA = has_next ? (const char*)g.A + (size_t)nxt.bz * g.strideA * 2 + (size_t)nxt.pm * tstepA : cA;
;         const char* nB = has_next ? (const char*)g.Bt + (size_t)nxt.bz * g.strideB * 2 + (size_t)nxt.pn * tstepB : cB;
;     ...
; #pragma unroll
;         for (int a = 0; a < 2; ++a)
; #pragma unroll
;             for (int b = 0; b < 2; ++b)
; #pragma unroll
;                 for (int m = 0; m < 4; ++m)
; #pragma unroll
;                     for (int n = 0; n < 2; ++n) acc[a][b][m][n] = (f32x4){0.f, 0.f, 0.f, 0.f};
.LBB0_111:
	s_ashr_i32 s69, s68, 31
	s_lshl_b64 s[12:13], s[68:69], 18
	s_add_u32 s86, s34, s12
	s_addc_u32 s87, s35, s13
	s_and_b64 s[12:13], s[40:41], exec
	s_cselect_b32 s11, s87, s23
	s_cselect_b32 s12, s86, s22
	s_ashr_i32 s83, s82, 31
	s_lshl_b64 s[30:31], s[82:83], 18
	s_add_u32 s36, s4, s30
	s_addc_u32 s37, s5, s31
	s_and_b64 s[30:31], s[40:41], exec
	s_cselect_b32 s13, s37, s39
	s_cselect_b32 s21, s36, s38
	s_add_u32 s22, s22, 0x20080
	s_addc_u32 s23, s23, 0
	s_add_u32 s30, s38, 0x100
	v_mov_b64_e32 v[0:1], 0
	v_mov_b64_e32 v[2:3], 0
	v_mov_b64_e32 v[4:5], 0
	v_mov_b64_e32 v[6:7], 0
	v_mov_b64_e32 v[8:9], 0
	v_mov_b64_e32 v[10:11], 0
	v_mov_b64_e32 v[12:13], 0
	v_mov_b64_e32 v[14:15], 0
	v_mov_b64_e32 v[16:17], 0
	v_mov_b64_e32 v[18:19], 0
	v_mov_b64_e32 v[20:21], 0
	v_mov_b64_e32 v[22:23], 0
	v_mov_b64_e32 v[24:25], 0
	v_mov_b64_e32 v[26:27], 0
	v_mov_b64_e32 v[28:29], 0
	v_mov_b64_e32 v[30:31], 0
	v_mov_b64_e32 v[32:33], 0
	v_mov_b64_e32 v[34:35], 0
	v_mov_b64_e32 v[36:37], 0
	v_mov_b64_e32 v[38:39], 0
	v_mov_b64_e32 v[40:41], 0
	v_mov_b64_e32 v[42:43], 0
	v_mov_b64_e32 v[44:45], 0
	v_mov_b64_e32 v[46:47], 0
	v_mov_b64_e32 v[48:49], 0
	v_mov_b64_e32 v[50:51], 0
	v_mov_b64_e32 v[52:53], 0
	v_mov_b64_e32 v[54:55], 0
	v_mov_b64_e32 v[56:57], 0
	v_mov_b64_e32 v[58:59], 0
	v_mov_b64_e32 v[60:61], 0
	v_mov_b64_e32 v[62:63], 0
	v_mov_b64_e32 v[64:65], 0
	v_mov_b64_e32 v[66:67], 0
	v_mov_b64_e32 v[68:69], 0
	v_mov_b64_e32 v[70:71], 0
	v_mov_b64_e32 v[72:73], 0
	v_mov_b64_e32 v[74:75], 0
	v_mov_b64_e32 v[76:77], 0
	v_mov_b64_e32 v[78:79], 0
	v_mov_b64_e32 v[80:81], 0
	v_mov_b64_e32 v[82:83], 0
	v_mov_b64_e32 v[84:85], 0
	v_mov_b64_e32 v[86:87], 0
	v_mov_b64_e32 v[88:89], 0
	v_mov_b64_e32 v[90:91], 0
	v_mov_b64_e32 v[92:93], 0
	v_mov_b64_e32 v[94:95], 0
	v_mov_b64_e32 v[96:97], 0
	v_mov_b64_e32 v[98:99], 0
	v_mov_b64_e32 v[100:101], 0
	v_mov_b64_e32 v[102:103], 0
	v_mov_b64_e32 v[104:105], 0
	v_mov_b64_e32 v[106:107], 0
	v_mov_b64_e32 v[108:109], 0
	v_mov_b64_e32 v[110:111], 0
	v_mov_b64_e32 v[112:113], 0
	v_mov_b64_e32 v[114:115], 0
	v_mov_b64_e32 v[116:117], 0
	v_mov_b64_e32 v[118:119], 0
	v_mov_b64_e32 v[120:121], 0
	v_mov_b64_e32 v[122:123], 0
	v_mov_b64_e32 v[124:125], 0
	v_mov_b64_e32 v[126:127], 0
	v_mov_b32_e32 v190, 0xbb00200b
	v_mov_b32_e32 v229, 0xbb80402b
	s_addc_u32 s31, s39, 0
	s_mov_b32 s43, -2

; __device__ __forceinline__ int obid() { int t = blockIdx.x; asm volatile("" : "+s"(t)); return t; }
; __global__ void __launch_bounds__(NTHR, 2) mega(Params Pval, int ph0, int ph1) {
;     ...
;             if (EN(16)) { pg8::Gemm g{(const bf16_t*)(ws + OFF_AS5), (const bf16_t*)(ws + OFF_H), 1280, 1024, 1024, 4, 1, 32, (size_t)1024 * 1280, (size_t)256 * 1024}; EpiS5E e{(float*)(ws + OFF_E)}; pg8::gemm_phase(lds, g, e); }
;             __syncthreads();
;             if (EN(17)) for (int u = obid(); u < 4096; u += gridDim.x) gla_a_unit(P, u, lds);
.LBB0_204:
	s_cmpk_lg_i32 s16, 0x100
	s_cbranch_scc1 .Lgla_orig_test
	s_cmpk_lt_i32 s2, 0x80
	s_cbranch_scc1 .Lgla_low
	s_cmpk_gt_i32 s17, 0xfff
	s_cbranch_scc0 .Lgla_go
	s_sub_i32 s18, s17, 0x1000
	s_cmp_eq_u32 s18, s2
	s_cbranch_scc0 .LBB0_225
	s_sub_i32 s17, s17, 0x280
	s_branch .Lgla_go
.Lgla_low:
	s_cmpk_gt_i32 s17, 0xdff
	s_cbranch_scc1 .LBB0_225
	s_branch .Lgla_go

; #define LAS __attribute__((address_space(3)))
; __device__ __forceinline__ int otid() { int t = threadIdx.x; asm volatile("" : "+v"(t)); return t; }
; __device__ __forceinline__ float bflo(unsigned w) { return __uint_as_float(w << 16); }
; __device__ __forceinline__ float bfhi(unsigned w) { return __uint_as_float(w & 0xffff0000u); }
; __device__ __forceinline__ void lds_barrier() { asm volatile("s_waitcnt lgkmcnt(0)" ::: "memory"); __builtin_amdgcn_s_barrier(); asm volatile("" ::: "memory"); }
; __device__ __forceinline__ void gla_gates(CP P, const bf16_t* PQ, int m0, int h, LAS unsigned char* lds) {
;     ...
;     { const int idx = tid * 4, t = idx >> 5, r = idx & 31; const uint2 raw = *(const uint2*)(PQ + (size_t)(m0 + t) * 1792 + 1536 + r);
;         *(LAS f32x4*)(gl + idx) = (f32x4){bflo(raw.x), bfhi(raw.x), bflo(raw.y), bfhi(raw.y)}; }
;     float w[16];
; #pragma unroll
;     for (int r = 0; r < 16; ++r) w[r] = P->in[18][(dir * 16 + r) * 256 + h * 64 + d];
;     const float b = P->in[19][dir * 256 + h * 64 + d];
;     lds_barrier();
;     float c[16];
; #pragma unroll
;     for (int i = 0; i < 16; ++i) { const int t = tq * 16 + i; float z = b;
; #pragma unroll
;         for (int r4 = 0; r4 < 4; ++r4) { const f32x4 g4 = *(const LAS f32x4*)(gl + t * 32 + dir * 16 + r4 * 4);
;             z += g4[0] * w[r4 * 4] + g4[1] * w[r4 * 4 + 1] + g4[2] * w[r4 * 4 + 2] + g4[3] * w[r4 * 4 + 3]; }
; __device__ void gla_a_unit(CP P, int unit, LAS unsigned char* lds) {
;     const int c = unit & 127, h = (unit >> 7) & 3, b = unit >> 9, m0 = b * 8192 + c * 64;
;     const bf16_t* PQ = (const bf16_t*)(P->ws + OFF_PQ); bf16_t* GST = (bf16_t*)(P->ws + OFF_GST); float* GDEC = (float*)(P->ws + OFF_GDEC);
;     const int tid = otid(), lane = tid & 63, wid = tid >> 6;
;     const int t = tid >> 3, d8 = (tid & 7) * 8, v16 = (tid & 7) * 16;
;     const uint4 kraw = *(const uint4*)(PQ + (size_t)(m0 + t) * 1792 + 256 + h * 64 + d8);
;     const uint4 vr0 = *(const uint4*)(PQ + (size_t)(m0 + t) * 1792 + 512 + h * 128 + v16), vr1 = *(const uint4*)(PQ + (size_t)(m0 + t) * 1792 + 512 + h * 128 + v16 + 8);
;     gla_gates(P, PQ, m0, h, lds);
.Lgla_go:
	s_and_b32 s18, s17, 0x7f
	s_ashr_i32 s11, s17, 9
	s_lshl_b32 s12, s11, 13
	s_lshl_b32 s13, s18, 6
	v_mov_b32_e32 v44, v191
	s_or_b32 s19, s12, s13
	s_bfe_u32 s10, s17, 0x20007
	v_ashrrev_i32_e32 v45, 3, v44
	v_add_u32_e32 v0, s19, v45
	v_mov_b64_e32 v[14:15], s[14:15]
	v_and_b32_e32 v46, 7, v44
	v_mad_i64_i32 v[0:1], s[12:13], v0, s81, v[14:15]
	s_lshl_b32 s66, s10, 7
	v_lshlrev_b32_e32 v12, 4, v46
	v_lshl_add_u64 v[2:3], v[0:1], 0, s[66:67]
	v_mov_b32_e32 v13, v184
	v_lshl_add_u64 v[2:3], v[2:3], 0, v[12:13]
	s_lshl_b32 s66, s10, 8
	v_mov_b64_e32 v[102:103], v[2:3]
	v_lshl_add_u64 v[0:1], v[0:1], 0, s[66:67]
	v_lshlrev_b32_e32 v2, 5, v46
	v_mov_b32_e32 v3, v184
	v_lshl_add_u64 v[4:5], v[0:1], 0, v[2:3]
	v_mov_b32_e32 v49, v191
	v_mov_b32_e32 v17, v184
	v_ashrrev_i32_e32 v16, 3, v49
	v_add_u32_e32 v16, s19, v16
	v_mad_i64_i32 v[14:15], s[20:21], v16, s81, v[14:15]
	v_lshlrev_b32_e32 v16, 3, v49
	v_and_b32_e32 v16, 56, v16
	v_lshl_add_u64 v[14:15], v[14:15], 0, v[16:17]
	global_load_dwordx2 v[16:17], v[14:15], off offset:3072
	s_load_dwordx4 s[20:23], s[0:1], 0x90
	v_ashrrev_i32_e32 v13, 8, v49
	v_lshl_add_u32 v18, v49, 4, 0
	s_lshl_b32 s12, s10, 6
	v_and_b32_e32 v47, 63, v49
	s_movk_i32 s13, 0x1000
	v_and_b32_e32 v50, 0xffffff00, v49
	s_waitcnt lgkmcnt(0)
	v_mov_b32_e32 v30, s22
	v_mov_b32_e32 v31, s23
	v_bfe_u32 v48, v49, 6, 2
	s_waitcnt vmcnt(0)
	v_lshlrev_b32_e32 v14, 16, v16
	v_and_b32_e32 v15, 0xffff0000, v16
	v_lshlrev_b32_e32 v16, 16, v17
	v_and_b32_e32 v17, 0xffff0000, v17
	ds_write_b128 v18, v[14:17]
	v_lshlrev_b32_e32 v16, 12, v13
	v_or3_b32 v16, v16, s12, v47
	v_mov_b32_e32 v14, s20
	v_mov_b32_e32 v15, s21
	v_ashrrev_i32_e32 v17, 31, v16
	v_lshl_add_u64 v[32:33], v[16:17], 2, v[14:15]
	v_add_co_u32_e32 v16, vcc, s13, v32
	s_movk_i32 s13, 0x3000
	s_nop 0
	v_addc_co_u32_e32 v17, vcc, 0, v33, vcc
	v_add_co_u32_e32 v34, vcc, s88, v32
	global_load_dword v20, v[32:33], off
	global_load_dword v24, v[32:33], off offset:1024
	global_load_dword v18, v[32:33], off offset:2048
	global_load_dword v14, v[32:33], off offset:3072
	v_addc_co_u32_e32 v35, vcc, 0, v33, vcc
	v_add_co_u32_e32 v32, vcc, s13, v32
	global_load_dword v21, v[34:35], off offset:-4096
	global_load_dword v25, v[16:17], off offset:1024
	global_load_dword v19, v[16:17], off offset:2048
	global_load_dword v15, v[16:17], off offset:3072
	global_load_dword v26, v[34:35], off
	global_load_dword v28, v[34:35], off offset:1024
	global_load_dword v22, v[34:35], off offset:2048
	s_nop 0
	global_load_dword v16, v[34:35], off offset:3072
	v_addc_co_u32_e32 v33, vcc, 0, v33, vcc
	global_load_dword v27, v[32:33], off
	global_load_dword v29, v[32:33], off offset:1024
	global_load_dword v23, v[32:33], off offset:2048
	global_load_dword v17, v[32:33], off offset:3072
	v_or3_b32 v32, v47, s12, v50
	v_ashrrev_i32_e32 v33, 31, v32
	v_lshl_add_u64 v[30:31], v[32:33], 2, v[30:31]
	global_load_dword v51, v[30:31], off
	global_load_dwordx4 v[8:11], v[102:103], off offset:512
	global_load_dwordx4 v[0:3], v[4:5], off offset:1040
	s_nop 0
	global_load_dwordx4 v[4:7], v[4:5], off offset:1024
	v_lshlrev_b32_e32 v30, 11, v48
	v_lshlrev_b32_e32 v31, 6, v13
	s_waitcnt lgkmcnt(0)
	s_barrier
	v_add3_u32 v52, 0, v30, v31
	ds_read_b128 v[30:33], v52
	ds_read_b128 v[34:37], v52 offset:16
	ds_read_b128 v[38:41], v52 offset:32
	ds_read_b128 v[54:57], v52 offset:48
	s_movk_i32 s12, 0x100
	s_waitcnt lgkmcnt(3)
	v_mov_b32_e32 v42, v30
	s_waitcnt lgkmcnt(2)
	v_mov_b32_e32 v43, v34
	v_mov_b32_e32 v34, v31
	s_waitcnt vmcnt(14)
	v_pk_mul_f32 v[30:31], v[24:25], v[34:35]
	s_nop 0
	v_pk_fma_f32 v[30:31], v[20:21], v[42:43], v[30:31]
	v_mov_b32_e32 v34, v32
	v_mov_b32_e32 v35, v36
	s_waitcnt vmcnt(13)
	v_pk_fma_f32 v[30:31], v[18:19], v[34:35], v[30:31]
	v_mov_b32_e32 v36, v33
	s_waitcnt vmcnt(12)
	v_pk_fma_f32 v[30:31], v[14:15], v[36:37], v[30:31]
	s_waitcnt vmcnt(3)
	v_add_f32_e32 v30, v51, v30
	v_add_f32_e32 v34, v30, v31
	s_waitcnt lgkmcnt(0)
	v_mov_b32_e32 v31, v54
	v_mov_b32_e32 v54, v39
	v_mov_b32_e32 v30, v38
	v_pk_mul_f32 v[32:33], v[28:29], v[54:55]
	s_nop 0
	v_pk_fma_f32 v[30:31], v[26:27], v[30:31], v[32:33]
	v_mov_b32_e32 v32, v40
	v_mov_b32_e32 v33, v56
	v_pk_fma_f32 v[30:31], v[22:23], v[32:33], v[30:31]
	v_mov_b32_e32 v56, v41
	v_pk_fma_f32 v[30:31], v[16:17], v[56:57], v[30:31]
	s_nop 0
	v_add_f32_e32 v30, v34, v30
	v_add_f32_e32 v30, v30, v31
	v_min_f32_e32 v38, 0, v30
	v_mul_f32_e64 v30, |v30|, s33
	v_exp_f32_e32 v30, v30
	s_nop 0
	v_add_f32_e32 v30, 1.0, v30
	v_cmp_gt_f32_e32 vcc, s80, v30
	s_nop 1
	v_cndmask_b32_e64 v31, 0, 32, vcc
	v_ldexp_f32 v30, v30, v31
	v_log_f32_e32 v30, v30
	s_nop 0
	v_mul_f32_e32 v31, 0x3f317217, v30
	v_fma_f32 v31, v30, s92, -v31
	v_fmac_f32_e32 v31, 0x3377d1cf, v30
	v_fmac_f32_e32 v31, 0x3f317217, v30
	v_cmp_lt_f32_e64 s[40:41], |v30|, s93
	s_nop 1
	v_cndmask_b32_e64 v30, v30, v31, s[40:41]
	v_cndmask_b32_e32 v31, 0, v231, vcc
	v_sub_f32_e32 v40, v30, v31
	ds_read_b128 v[30:33], v52 offset:128
	ds_read_b128 v[34:37], v52 offset:144
	s_waitcnt lgkmcnt(1)
	v_mov_b32_e32 v42, v30
	s_waitcnt lgkmcnt(0)
	v_mov_b32_e32 v43, v34
	v_mov_b32_e32 v34, v31
	v_pk_mul_f32 v[30:31], v[24:25], v[34:35]
	v_mov_b32_e32 v34, v32
	v_pk_fma_f32 v[30:31], v[20:21], v[42:43], v[30:31]
	v_mov_b32_e32 v35, v36
	v_pk_fma_f32 v[30:31], v[18:19], v[34:35], v[30:31]
	v_mov_b32_e32 v36, v33
	v_pk_fma_f32 v[30:31], v[14:15], v[36:37], v[30:31]
	s_nop 0
	v_add_f32_e32 v30, v51, v30
	v_add_f32_e32 v39, v30, v31
	ds_read_b128 v[30:33], v52 offset:160
	ds_read_b128 v[34:37], v52 offset:176
	s_waitcnt lgkmcnt(1)
	v_mov_b32_e32 v42, v30
	s_waitcnt lgkmcnt(0)
; #define LAS __attribute__((address_space(3)))
; __device__ __forceinline__ void gla_gates(CP P, const bf16_t* PQ, int m0, int h, LAS unsigned char* lds) {
;     ...
;     for (int i = 0; i < 16; ++i) { const int t = tq * 16 + i; float z = b;
; #pragma unroll
;         for (int r4 = 0; r4 < 4; ++r4) { const f32x4 g4 = *(const LAS f32x4*)(gl + t * 32 + dir * 16 + r4 * 4);
;             z += g4[0] * w[r4 * 4] + g4[1] * w[r4 * 4 + 1] + g4[2] * w[r4 * 4 + 2] + g4[3] * w[r4 * 4 + 3]; }
;         c[i] = (fminf(z, 0.f) - __logf(1.0f + __expf(-fabsf(z)))) * (1.0f / 16.0f); }
	v_mov_b32_e32 v43, v34
	v_mov_b32_e32 v34, v31
	v_pk_mul_f32 v[30:31], v[28:29], v[34:35]
	v_mov_b32_e32 v34, v32
	v_pk_fma_f32 v[30:31], v[26:27], v[42:43], v[30:31]
	v_mov_b32_e32 v35, v36
	v_pk_fma_f32 v[30:31], v[22:23], v[34:35], v[30:31]
	v_mov_b32_e32 v36, v33
	v_pk_fma_f32 v[30:31], v[16:17], v[36:37], v[30:31]
	s_nop 0
	v_add_f32_e32 v30, v39, v30
	v_add_f32_e32 v30, v30, v31
	v_min_f32_e32 v39, 0, v30
	v_mul_f32_e64 v30, |v30|, s33
	v_exp_f32_e32 v30, v30
	s_nop 0
	v_add_f32_e32 v30, 1.0, v30
	v_cmp_gt_f32_e32 vcc, s80, v30
	s_nop 1
	v_cndmask_b32_e64 v31, 0, 32, vcc
	v_ldexp_f32 v30, v30, v31
	v_log_f32_e32 v30, v30
	s_nop 0
	v_mul_f32_e32 v31, 0x3f317217, v30
	v_fma_f32 v31, v30, s92, -v31
	v_fmac_f32_e32 v31, 0x3377d1cf, v30
	v_fmac_f32_e32 v31, 0x3f317217, v30
	v_cmp_lt_f32_e64 s[40:41], |v30|, s93
	s_nop 1
	v_cndmask_b32_e64 v30, v30, v31, s[40:41]
	v_cndmask_b32_e32 v31, 0, v231, vcc
	v_sub_f32_e32 v41, v30, v31
	v_pk_add_f32 v[30:31], v[38:39], v[40:41] neg_lo:[0,1] neg_hi:[0,1]
	ds_read_b128 v[32:35], v52 offset:256
	ds_read_b128 v[36:39], v52 offset:272
	v_pk_mul_f32 v[30:31], v[30:31], s[78:79] op_sel_hi:[1,0]
	s_waitcnt lgkmcnt(1)
	v_mov_b32_e32 v40, v32
	s_waitcnt lgkmcnt(0)
	v_mov_b32_e32 v41, v36
	v_mov_b32_e32 v36, v33
	v_pk_mul_f32 v[32:33], v[24:25], v[36:37]
	v_mov_b32_e32 v36, v34
	v_pk_fma_f32 v[32:33], v[20:21], v[40:41], v[32:33]
	v_mov_b32_e32 v37, v38
	v_pk_fma_f32 v[32:33], v[18:19], v[36:37], v[32:33]
	v_mov_b32_e32 v38, v35
	v_pk_fma_f32 v[32:33], v[14:15], v[38:39], v[32:33]
	s_nop 0
	v_add_f32_e32 v32, v51, v32
	v_add_f32_e32 v42, v32, v33
	ds_read_b128 v[32:35], v52 offset:288
	ds_read_b128 v[36:39], v52 offset:304
	s_waitcnt lgkmcnt(1)
	v_mov_b32_e32 v40, v32
	s_waitcnt lgkmcnt(0)
	v_mov_b32_e32 v41, v36
	v_mov_b32_e32 v36, v33
	v_pk_mul_f32 v[32:33], v[28:29], v[36:37]
	v_mov_b32_e32 v36, v34
	v_pk_fma_f32 v[32:33], v[26:27], v[40:41], v[32:33]
	v_mov_b32_e32 v37, v38
	v_pk_fma_f32 v[32:33], v[22:23], v[36:37], v[32:33]
	v_mov_b32_e32 v38, v35
	v_pk_fma_f32 v[32:33], v[16:17], v[38:39], v[32:33]
	s_nop 0
	v_add_f32_e32 v32, v42, v32
	v_add_f32_e32 v32, v32, v33
	v_min_f32_e32 v40, 0, v32
	v_mul_f32_e64 v32, |v32|, s33
	v_exp_f32_e32 v32, v32
	s_nop 0
	v_add_f32_e32 v32, 1.0, v32
	v_cmp_gt_f32_e32 vcc, s80, v32
	s_nop 1
	v_cndmask_b32_e64 v33, 0, 32, vcc
	v_ldexp_f32 v32, v32, v33
	v_log_f32_e32 v32, v32
	s_nop 0
	v_mul_f32_e32 v33, 0x3f317217, v32
	v_fma_f32 v33, v32, s92, -v33
	v_fmac_f32_e32 v33, 0x3377d1cf, v32
	v_fmac_f32_e32 v33, 0x3f317217, v32
	v_cmp_lt_f32_e64 s[40:41], |v32|, s93
	s_nop 1
	v_cndmask_b32_e64 v32, v32, v33, s[40:41]
	v_cndmask_b32_e32 v33, 0, v231, vcc
	v_sub_f32_e32 v42, v32, v33
	ds_read_b128 v[32:35], v52 offset:384
	ds_read_b128 v[36:39], v52 offset:400
	s_waitcnt lgkmcnt(1)
	v_mov_b32_e32 v54, v32
	s_waitcnt lgkmcnt(0)
	v_mov_b32_e32 v55, v36
	v_mov_b32_e32 v36, v33
	v_pk_mul_f32 v[32:33], v[24:25], v[36:37]
	v_mov_b32_e32 v36, v34
	v_pk_fma_f32 v[32:33], v[20:21], v[54:55], v[32:33]
	v_mov_b32_e32 v37, v38
	v_pk_fma_f32 v[32:33], v[18:19], v[36:37], v[32:33]
	v_mov_b32_e32 v38, v35
	v_pk_fma_f32 v[32:33], v[14:15], v[38:39], v[32:33]
	s_nop 0
	v_add_f32_e32 v32, v51, v32
	v_add_f32_e32 v41, v32, v33
	ds_read_b128 v[32:35], v52 offset:416
	ds_read_b128 v[36:39], v52 offset:432
	s_waitcnt lgkmcnt(1)
	v_mov_b32_e32 v54, v32
	s_waitcnt lgkmcnt(0)
	v_mov_b32_e32 v55, v36
	v_mov_b32_e32 v36, v33
	v_pk_mul_f32 v[32:33], v[28:29], v[36:37]
	v_mov_b32_e32 v36, v34
	v_pk_fma_f32 v[32:33], v[26:27], v[54:55], v[32:33]
	v_mov_b32_e32 v37, v38
	v_pk_fma_f32 v[32:33], v[22:23], v[36:37], v[32:33]
	v_mov_b32_e32 v38, v35
	v_pk_fma_f32 v[32:33], v[16:17], v[38:39], v[32:33]
	s_nop 0
	v_add_f32_e32 v32, v41, v32
	v_add_f32_e32 v32, v32, v33
	v_min_f32_e32 v41, 0, v32
	v_mul_f32_e64 v32, |v32|, s33
	v_exp_f32_e32 v32, v32
	s_nop 0
	v_add_f32_e32 v32, 1.0, v32
	v_cmp_gt_f32_e32 vcc, s80, v32
	s_nop 1
	v_cndmask_b32_e64 v33, 0, 32, vcc
	v_ldexp_f32 v32, v32, v33
	v_log_f32_e32 v32, v32
	s_nop 0
	v_mul_f32_e32 v33, 0x3f317217, v32
	v_fma_f32 v33, v32, s92, -v33
	v_fmac_f32_e32 v33, 0x3377d1cf, v32
	v_fmac_f32_e32 v33, 0x3f317217, v32
	v_cmp_lt_f32_e64 s[40:41], |v32|, s93
	s_nop 1
	v_cndmask_b32_e64 v32, v32, v33, s[40:41]
	v_cndmask_b32_e32 v33, 0, v231, vcc
	v_sub_f32_e32 v43, v32, v33
	v_pk_add_f32 v[32:33], v[40:41], v[42:43] neg_lo:[0,1] neg_hi:[0,1]
	ds_read_b128 v[34:37], v52 offset:512
	ds_read_b128 v[38:41], v52 offset:528
	v_pk_mul_f32 v[32:33], v[32:33], s[78:79] op_sel_hi:[1,0]
	s_waitcnt lgkmcnt(1)
	v_mov_b32_e32 v42, v34
	s_waitcnt lgkmcnt(0)
	v_mov_b32_e32 v43, v38
	v_mov_b32_e32 v38, v35
	v_pk_mul_f32 v[34:35], v[24:25], v[38:39]
	v_mov_b32_e32 v38, v36
	v_pk_fma_f32 v[34:35], v[20:21], v[42:43], v[34:35]
	v_mov_b32_e32 v39, v40
	v_pk_fma_f32 v[34:35], v[18:19], v[38:39], v[34:35]
	v_mov_b32_e32 v40, v37
	v_pk_fma_f32 v[34:35], v[14:15], v[40:41], v[34:35]
	s_nop 0
	v_add_f32_e32 v34, v51, v34
	v_add_f32_e32 v53, v34, v35
	ds_read_b128 v[34:37], v52 offset:544
	ds_read_b128 v[38:41], v52 offset:560
	s_waitcnt lgkmcnt(1)
	v_mov_b32_e32 v42, v34
	s_waitcnt lgkmcnt(0)
; #define LAS __attribute__((address_space(3)))
; __device__ __forceinline__ void gla_gates(CP P, const bf16_t* PQ, int m0, int h, LAS unsigned char* lds) {
;     ...
;     for (int i = 0; i < 16; ++i) { const int t = tq * 16 + i; float z = b;
; #pragma unroll
;         for (int r4 = 0; r4 < 4; ++r4) { const f32x4 g4 = *(const LAS f32x4*)(gl + t * 32 + dir * 16 + r4 * 4);
;             z += g4[0] * w[r4 * 4] + g4[1] * w[r4 * 4 + 1] + g4[2] * w[r4 * 4 + 2] + g4[3] * w[r4 * 4 + 3]; }
;         c[i] = (fminf(z, 0.f) - __logf(1.0f + __expf(-fabsf(z)))) * (1.0f / 16.0f); }
	v_mov_b32_e32 v43, v38
	v_mov_b32_e32 v38, v35
	v_pk_mul_f32 v[34:35], v[28:29], v[38:39]
	v_mov_b32_e32 v38, v36
	v_pk_fma_f32 v[34:35], v[26:27], v[42:43], v[34:35]
	v_mov_b32_e32 v39, v40
	v_pk_fma_f32 v[34:35], v[22:23], v[38:39], v[34:35]
	v_mov_b32_e32 v40, v37
	v_pk_fma_f32 v[34:35], v[16:17], v[40:41], v[34:35]
	s_nop 0
	v_add_f32_e32 v34, v53, v34
	v_add_f32_e32 v34, v34, v35
	v_min_f32_e32 v42, 0, v34
	v_mul_f32_e64 v34, |v34|, s33
	v_exp_f32_e32 v34, v34
	s_nop 0
	v_add_f32_e32 v34, 1.0, v34
	v_cmp_gt_f32_e32 vcc, s80, v34
	s_nop 1
	v_cndmask_b32_e64 v35, 0, 32, vcc
	v_ldexp_f32 v34, v34, v35
	v_log_f32_e32 v34, v34
	s_nop 0
	v_mul_f32_e32 v35, 0x3f317217, v34
	v_fma_f32 v35, v34, s92, -v35
	v_fmac_f32_e32 v35, 0x3377d1cf, v34
	v_fmac_f32_e32 v35, 0x3f317217, v34
	v_cmp_lt_f32_e64 s[40:41], |v34|, s93
	s_nop 1
	v_cndmask_b32_e64 v34, v34, v35, s[40:41]
	v_cndmask_b32_e32 v35, 0, v231, vcc
	v_sub_f32_e32 v54, v34, v35
	ds_read_b128 v[34:37], v52 offset:640
	ds_read_b128 v[38:41], v52 offset:656
	s_waitcnt lgkmcnt(1)
	v_mov_b32_e32 v56, v34
	s_waitcnt lgkmcnt(0)
	v_mov_b32_e32 v57, v38
	v_mov_b32_e32 v38, v35
	v_pk_mul_f32 v[34:35], v[24:25], v[38:39]
	v_mov_b32_e32 v38, v36
	v_pk_fma_f32 v[34:35], v[20:21], v[56:57], v[34:35]
	v_mov_b32_e32 v39, v40
	v_pk_fma_f32 v[34:35], v[18:19], v[38:39], v[34:35]
	v_mov_b32_e32 v40, v37
	v_pk_fma_f32 v[34:35], v[14:15], v[40:41], v[34:35]
	s_nop 0
	v_add_f32_e32 v34, v51, v34
	v_add_f32_e32 v43, v34, v35
	ds_read_b128 v[34:37], v52 offset:672
	ds_read_b128 v[38:41], v52 offset:688
	s_waitcnt lgkmcnt(1)
	v_mov_b32_e32 v56, v34
	s_waitcnt lgkmcnt(0)
	v_mov_b32_e32 v57, v38
	v_mov_b32_e32 v38, v35
	v_pk_mul_f32 v[34:35], v[28:29], v[38:39]
	v_mov_b32_e32 v38, v36
	v_pk_fma_f32 v[34:35], v[26:27], v[56:57], v[34:35]
	v_mov_b32_e32 v39, v40
	v_pk_fma_f32 v[34:35], v[22:23], v[38:39], v[34:35]
	v_mov_b32_e32 v40, v37
	v_pk_fma_f32 v[34:35], v[16:17], v[40:41], v[34:35]
	s_nop 0
	v_add_f32_e32 v34, v43, v34
	v_add_f32_e32 v34, v34, v35
	v_min_f32_e32 v43, 0, v34
	v_mul_f32_e64 v34, |v34|, s33
	v_exp_f32_e32 v34, v34
	s_nop 0
	v_add_f32_e32 v34, 1.0, v34
	v_cmp_gt_f32_e32 vcc, s80, v34
	s_nop 1
	v_cndmask_b32_e64 v35, 0, 32, vcc
	v_ldexp_f32 v34, v34, v35
	v_log_f32_e32 v34, v34
	s_nop 0
	v_mul_f32_e32 v35, 0x3f317217, v34
	v_fma_f32 v35, v34, s92, -v35
	v_fmac_f32_e32 v35, 0x3377d1cf, v34
	v_fmac_f32_e32 v35, 0x3f317217, v34
	v_cmp_lt_f32_e64 s[40:41], |v34|, s93
	s_nop 1
	v_cndmask_b32_e64 v34, v34, v35, s[40:41]
	v_cndmask_b32_e32 v35, 0, v231, vcc
	v_sub_f32_e32 v55, v34, v35
	v_pk_add_f32 v[34:35], v[42:43], v[54:55] neg_lo:[0,1] neg_hi:[0,1]
	ds_read_b128 v[36:39], v52 offset:768
	ds_read_b128 v[40:43], v52 offset:784
	v_pk_mul_f32 v[34:35], v[34:35], s[78:79] op_sel_hi:[1,0]
	s_waitcnt lgkmcnt(1)
	v_mov_b32_e32 v54, v36
	s_waitcnt lgkmcnt(0)
	v_mov_b32_e32 v55, v40
	v_mov_b32_e32 v40, v37
	v_pk_mul_f32 v[36:37], v[24:25], v[40:41]
	v_mov_b32_e32 v40, v38
	v_pk_fma_f32 v[36:37], v[20:21], v[54:55], v[36:37]
	v_mov_b32_e32 v41, v42
	v_pk_fma_f32 v[36:37], v[18:19], v[40:41], v[36:37]
	v_mov_b32_e32 v42, v39
	v_pk_fma_f32 v[36:37], v[14:15], v[42:43], v[36:37]
	s_nop 0
	v_add_f32_e32 v36, v51, v36
	v_add_f32_e32 v53, v36, v37
	ds_read_b128 v[36:39], v52 offset:800
	ds_read_b128 v[40:43], v52 offset:816
	s_waitcnt lgkmcnt(1)
	v_mov_b32_e32 v54, v36
	s_waitcnt lgkmcnt(0)
	v_mov_b32_e32 v55, v40
	v_mov_b32_e32 v40, v37
	v_pk_mul_f32 v[36:37], v[28:29], v[40:41]
	v_mov_b32_e32 v40, v38
	v_pk_fma_f32 v[36:37], v[26:27], v[54:55], v[36:37]
	v_mov_b32_e32 v41, v42
	v_pk_fma_f32 v[36:37], v[22:23], v[40:41], v[36:37]
	v_mov_b32_e32 v42, v39
	v_pk_fma_f32 v[36:37], v[16:17], v[42:43], v[36:37]
	s_nop 0
	v_add_f32_e32 v36, v53, v36
	v_add_f32_e32 v36, v36, v37
	v_min_f32_e32 v54, 0, v36
	v_mul_f32_e64 v36, |v36|, s33
	v_exp_f32_e32 v36, v36
	s_nop 0
	v_add_f32_e32 v36, 1.0, v36
	v_cmp_gt_f32_e32 vcc, s80, v36
	s_nop 1
	v_cndmask_b32_e64 v37, 0, 32, vcc
	v_ldexp_f32 v36, v36, v37
	v_log_f32_e32 v36, v36
	s_nop 0
	v_mul_f32_e32 v37, 0x3f317217, v36
	v_fma_f32 v37, v36, s92, -v37
	v_fmac_f32_e32 v37, 0x3377d1cf, v36
	v_fmac_f32_e32 v37, 0x3f317217, v36
	v_cmp_lt_f32_e64 s[40:41], |v36|, s93
	s_nop 1
	v_cndmask_b32_e64 v36, v36, v37, s[40:41]
	v_cndmask_b32_e32 v37, 0, v231, vcc
	v_sub_f32_e32 v56, v36, v37
	ds_read_b128 v[36:39], v52 offset:896
	ds_read_b128 v[40:43], v52 offset:912
	s_waitcnt lgkmcnt(1)
	v_mov_b32_e32 v58, v36
	s_waitcnt lgkmcnt(0)
	v_mov_b32_e32 v59, v40
	v_mov_b32_e32 v40, v37
	v_pk_mul_f32 v[36:37], v[24:25], v[40:41]
	v_mov_b32_e32 v40, v38
	v_pk_fma_f32 v[36:37], v[20:21], v[58:59], v[36:37]
	v_mov_b32_e32 v41, v42
	v_pk_fma_f32 v[36:37], v[18:19], v[40:41], v[36:37]
	v_mov_b32_e32 v42, v39
	v_pk_fma_f32 v[36:37], v[14:15], v[42:43], v[36:37]
	s_nop 0
	v_add_f32_e32 v36, v51, v36
	v_add_f32_e32 v53, v36, v37
	ds_read_b128 v[36:39], v52 offset:928
	ds_read_b128 v[40:43], v52 offset:944
	s_waitcnt lgkmcnt(1)
	v_mov_b32_e32 v58, v36
	s_waitcnt lgkmcnt(0)
	v_mov_b32_e32 v59, v40
	v_mov_b32_e32 v40, v37
	v_pk_mul_f32 v[36:37], v[28:29], v[40:41]
	v_mov_b32_e32 v40, v38
	v_pk_fma_f32 v[36:37], v[26:27], v[58:59], v[36:37]
	v_mov_b32_e32 v41, v42
	v_pk_fma_f32 v[36:37], v[22:23], v[40:41], v[36:37]
	v_mov_b32_e32 v42, v39
	v_pk_fma_f32 v[36:37], v[16:17], v[42:43], v[36:37]
	s_nop 0
	v_add_f32_e32 v36, v53, v36
	v_add_f32_e32 v36, v36, v37
	v_min_f32_e32 v55, 0, v36
	v_mul_f32_e64 v36, |v36|, s33
	v_exp_f32_e32 v36, v36
	s_nop 0
	v_add_f32_e32 v36, 1.0, v36
	v_cmp_gt_f32_e32 vcc, s80, v36
	s_nop 1
	v_cndmask_b32_e64 v37, 0, 32, vcc
	v_ldexp_f32 v36, v36, v37
	v_log_f32_e32 v36, v36
	s_nop 0
	v_mul_f32_e32 v37, 0x3f317217, v36
	v_fma_f32 v37, v36, s92, -v37
	v_fmac_f32_e32 v37, 0x3377d1cf, v36
	v_fmac_f32_e32 v37, 0x3f317217, v36
	v_cmp_lt_f32_e64 s[40:41], |v36|, s93
	s_nop 1
	v_cndmask_b32_e64 v36, v36, v37, s[40:41]
	v_cndmask_b32_e32 v37, 0, v231, vcc
	v_sub_f32_e32 v57, v36, v37
	v_pk_add_f32 v[36:37], v[54:55], v[56:57] neg_lo:[0,1] neg_hi:[0,1]
	ds_read_b128 v[38:41], v52 offset:1024
	ds_read_b128 v[54:57], v52 offset:1040
	v_pk_mul_f32 v[36:37], v[36:37], s[78:79] op_sel_hi:[1,0]
	s_waitcnt lgkmcnt(1)
; #define LAS __attribute__((address_space(3)))
; __device__ __forceinline__ void gla_gates(CP P, const bf16_t* PQ, int m0, int h, LAS unsigned char* lds) {
;     ...
;     for (int i = 0; i < 16; ++i) { const int t = tq * 16 + i; float z = b;
; #pragma unroll
;         for (int r4 = 0; r4 < 4; ++r4) { const f32x4 g4 = *(const LAS f32x4*)(gl + t * 32 + dir * 16 + r4 * 4);
;             z += g4[0] * w[r4 * 4] + g4[1] * w[r4 * 4 + 1] + g4[2] * w[r4 * 4 + 2] + g4[3] * w[r4 * 4 + 3]; }
;         c[i] = (fminf(z, 0.f) - __logf(1.0f + __expf(-fabsf(z)))) * (1.0f / 16.0f); }
	v_mov_b32_e32 v42, v38
	s_waitcnt lgkmcnt(0)
	v_mov_b32_e32 v43, v54
	v_mov_b32_e32 v54, v39
	v_pk_mul_f32 v[38:39], v[24:25], v[54:55]
	s_nop 0
	v_pk_fma_f32 v[38:39], v[20:21], v[42:43], v[38:39]
	v_mov_b32_e32 v42, v40
	v_mov_b32_e32 v43, v56
	v_pk_fma_f32 v[38:39], v[18:19], v[42:43], v[38:39]
	v_mov_b32_e32 v56, v41
	v_pk_fma_f32 v[38:39], v[14:15], v[56:57], v[38:39]
	s_nop 0
	v_add_f32_e32 v38, v51, v38
	v_add_f32_e32 v53, v38, v39
	ds_read_b128 v[38:41], v52 offset:1056
	ds_read_b128 v[54:57], v52 offset:1072
	s_waitcnt lgkmcnt(1)
	v_mov_b32_e32 v42, v38
	s_waitcnt lgkmcnt(0)
	v_mov_b32_e32 v43, v54
	v_mov_b32_e32 v54, v39
	v_pk_mul_f32 v[38:39], v[28:29], v[54:55]
	s_nop 0
	v_pk_fma_f32 v[38:39], v[26:27], v[42:43], v[38:39]
	v_mov_b32_e32 v42, v40
	v_mov_b32_e32 v43, v56
	v_pk_fma_f32 v[38:39], v[22:23], v[42:43], v[38:39]
	v_mov_b32_e32 v56, v41
	v_pk_fma_f32 v[38:39], v[16:17], v[56:57], v[38:39]
	s_nop 0
	v_add_f32_e32 v38, v53, v38
	v_add_f32_e32 v38, v38, v39
	v_min_f32_e32 v42, 0, v38
	v_mul_f32_e64 v38, |v38|, s33
	v_exp_f32_e32 v38, v38
	s_nop 0
	v_add_f32_e32 v38, 1.0, v38
	v_cmp_gt_f32_e32 vcc, s80, v38
	s_nop 1
	v_cndmask_b32_e64 v39, 0, 32, vcc
	v_ldexp_f32 v38, v38, v39
	v_log_f32_e32 v38, v38
	s_nop 0
	v_mul_f32_e32 v39, 0x3f317217, v38
	v_fma_f32 v39, v38, s92, -v39
	v_fmac_f32_e32 v39, 0x3377d1cf, v38
	v_fmac_f32_e32 v39, 0x3f317217, v38
	v_cmp_lt_f32_e64 s[40:41], |v38|, s93
	s_nop 1
	v_cndmask_b32_e64 v38, v38, v39, s[40:41]
	v_cndmask_b32_e32 v39, 0, v231, vcc
	v_sub_f32_e32 v58, v38, v39
	ds_read_b128 v[38:41], v52 offset:1152
	ds_read_b128 v[54:57], v52 offset:1168
	s_waitcnt lgkmcnt(1)
	v_mov_b32_e32 v60, v38
	s_waitcnt lgkmcnt(0)
	v_mov_b32_e32 v61, v54
	v_mov_b32_e32 v54, v39
	v_pk_mul_f32 v[38:39], v[24:25], v[54:55]
	v_mov_b32_e32 v54, v40
	v_pk_fma_f32 v[38:39], v[20:21], v[60:61], v[38:39]
	v_mov_b32_e32 v55, v56
	v_pk_fma_f32 v[38:39], v[18:19], v[54:55], v[38:39]
	v_mov_b32_e32 v56, v41
	v_pk_fma_f32 v[38:39], v[14:15], v[56:57], v[38:39]
	s_nop 0
	v_add_f32_e32 v38, v51, v38
	v_add_f32_e32 v43, v38, v39
	ds_read_b128 v[38:41], v52 offset:1184
	ds_read_b128 v[54:57], v52 offset:1200
	s_waitcnt lgkmcnt(1)
	v_mov_b32_e32 v60, v38
	s_waitcnt lgkmcnt(0)
	v_mov_b32_e32 v61, v54
	v_mov_b32_e32 v54, v39
	v_pk_mul_f32 v[38:39], v[28:29], v[54:55]
	v_mov_b32_e32 v54, v40
	v_pk_fma_f32 v[38:39], v[26:27], v[60:61], v[38:39]
	v_mov_b32_e32 v55, v56
	v_pk_fma_f32 v[38:39], v[22:23], v[54:55], v[38:39]
	v_mov_b32_e32 v56, v41
	v_pk_fma_f32 v[38:39], v[16:17], v[56:57], v[38:39]
	s_nop 0
	v_add_f32_e32 v38, v43, v38
	v_add_f32_e32 v38, v38, v39
	v_min_f32_e32 v43, 0, v38
	v_mul_f32_e64 v38, |v38|, s33
	v_exp_f32_e32 v38, v38
	s_nop 0
	v_add_f32_e32 v38, 1.0, v38
	v_cmp_gt_f32_e32 vcc, s80, v38
	s_nop 1
	v_cndmask_b32_e64 v39, 0, 32, vcc
	v_ldexp_f32 v38, v38, v39
	v_log_f32_e32 v38, v38
	s_nop 0
	v_mul_f32_e32 v39, 0x3f317217, v38
	v_fma_f32 v39, v38, s92, -v39
	v_fmac_f32_e32 v39, 0x3377d1cf, v38
	v_fmac_f32_e32 v39, 0x3f317217, v38
	v_cmp_lt_f32_e64 s[40:41], |v38|, s93
	s_nop 1
	v_cndmask_b32_e64 v38, v38, v39, s[40:41]
	v_cndmask_b32_e32 v39, 0, v231, vcc
	v_sub_f32_e32 v59, v38, v39
	v_pk_add_f32 v[38:39], v[42:43], v[58:59] neg_lo:[0,1] neg_hi:[0,1]
	ds_read_b128 v[40:43], v52 offset:1280
	ds_read_b128 v[54:57], v52 offset:1296
	v_pk_mul_f32 v[38:39], v[38:39], s[78:79] op_sel_hi:[1,0]
	s_waitcnt lgkmcnt(1)
	v_mov_b32_e32 v58, v40
	s_waitcnt lgkmcnt(0)
	v_mov_b32_e32 v59, v54
	v_mov_b32_e32 v54, v41
	v_pk_mul_f32 v[40:41], v[24:25], v[54:55]
	v_mov_b32_e32 v54, v42
	v_pk_fma_f32 v[40:41], v[20:21], v[58:59], v[40:41]
	v_mov_b32_e32 v55, v56
	v_pk_fma_f32 v[40:41], v[18:19], v[54:55], v[40:41]
	v_mov_b32_e32 v56, v43
	v_pk_fma_f32 v[40:41], v[14:15], v[56:57], v[40:41]
	s_nop 0
	v_add_f32_e32 v40, v51, v40
	v_add_f32_e32 v53, v40, v41
	ds_read_b128 v[40:43], v52 offset:1312
	ds_read_b128 v[54:57], v52 offset:1328
	s_waitcnt lgkmcnt(1)
	v_mov_b32_e32 v58, v40
	s_waitcnt lgkmcnt(0)
	v_mov_b32_e32 v59, v54
	v_mov_b32_e32 v54, v41
	v_pk_mul_f32 v[40:41], v[28:29], v[54:55]
	v_mov_b32_e32 v54, v42
	v_pk_fma_f32 v[40:41], v[26:27], v[58:59], v[40:41]
	v_mov_b32_e32 v55, v56
	v_pk_fma_f32 v[40:41], v[22:23], v[54:55], v[40:41]
	v_mov_b32_e32 v56, v43
	v_pk_fma_f32 v[40:41], v[16:17], v[56:57], v[40:41]
	s_nop 0
	v_add_f32_e32 v40, v53, v40
	v_add_f32_e32 v40, v40, v41
	v_min_f32_e32 v58, 0, v40
	v_mul_f32_e64 v40, |v40|, s33
	v_exp_f32_e32 v40, v40
	s_nop 0
	v_add_f32_e32 v40, 1.0, v40
	v_cmp_gt_f32_e32 vcc, s80, v40
	s_nop 1
	v_cndmask_b32_e64 v41, 0, 32, vcc
	v_ldexp_f32 v40, v40, v41
	v_log_f32_e32 v40, v40
	s_nop 0
	v_mul_f32_e32 v41, 0x3f317217, v40
	v_fma_f32 v41, v40, s92, -v41
	v_fmac_f32_e32 v41, 0x3377d1cf, v40
	v_fmac_f32_e32 v41, 0x3f317217, v40
	v_cmp_lt_f32_e64 s[40:41], |v40|, s93
	s_nop 1
	v_cndmask_b32_e64 v40, v40, v41, s[40:41]
	v_cndmask_b32_e32 v41, 0, v231, vcc
	v_sub_f32_e32 v60, v40, v41
	ds_read_b128 v[40:43], v52 offset:1408
	ds_read_b128 v[54:57], v52 offset:1424
	s_waitcnt lgkmcnt(1)
	v_mov_b32_e32 v62, v40
	s_waitcnt lgkmcnt(0)
	v_mov_b32_e32 v63, v54
	v_mov_b32_e32 v54, v41
	v_pk_mul_f32 v[40:41], v[24:25], v[54:55]
	v_mov_b32_e32 v54, v42
	v_pk_fma_f32 v[40:41], v[20:21], v[62:63], v[40:41]
	v_mov_b32_e32 v55, v56
	v_pk_fma_f32 v[40:41], v[18:19], v[54:55], v[40:41]
	v_mov_b32_e32 v56, v43
	v_pk_fma_f32 v[40:41], v[14:15], v[56:57], v[40:41]
	s_nop 0
	v_add_f32_e32 v40, v51, v40
	v_add_f32_e32 v53, v40, v41
	ds_read_b128 v[40:43], v52 offset:1440
	ds_read_b128 v[54:57], v52 offset:1456
	s_waitcnt lgkmcnt(1)
	v_mov_b32_e32 v62, v40
	s_waitcnt lgkmcnt(0)
; #define LAS __attribute__((address_space(3)))
; __device__ __forceinline__ void gla_gates(CP P, const bf16_t* PQ, int m0, int h, LAS unsigned char* lds) {
;     ...
;     for (int i = 0; i < 16; ++i) { const int t = tq * 16 + i; float z = b;
; #pragma unroll
;         for (int r4 = 0; r4 < 4; ++r4) { const f32x4 g4 = *(const LAS f32x4*)(gl + t * 32 + dir * 16 + r4 * 4);
;             z += g4[0] * w[r4 * 4] + g4[1] * w[r4 * 4 + 1] + g4[2] * w[r4 * 4 + 2] + g4[3] * w[r4 * 4 + 3]; }
;         c[i] = (fminf(z, 0.f) - __logf(1.0f + __expf(-fabsf(z)))) * (1.0f / 16.0f); }
	v_mov_b32_e32 v63, v54
	v_mov_b32_e32 v54, v41
	v_pk_mul_f32 v[40:41], v[28:29], v[54:55]
	v_mov_b32_e32 v54, v42
	v_pk_fma_f32 v[40:41], v[26:27], v[62:63], v[40:41]
	v_mov_b32_e32 v55, v56
	v_pk_fma_f32 v[40:41], v[22:23], v[54:55], v[40:41]
	v_mov_b32_e32 v56, v43
	v_pk_fma_f32 v[40:41], v[16:17], v[56:57], v[40:41]
	s_nop 0
	v_add_f32_e32 v40, v53, v40
	v_add_f32_e32 v40, v40, v41
	v_min_f32_e32 v59, 0, v40
	v_mul_f32_e64 v40, |v40|, s33
	v_exp_f32_e32 v40, v40
	s_nop 0
	v_add_f32_e32 v40, 1.0, v40
	v_cmp_gt_f32_e32 vcc, s80, v40
	s_nop 1
	v_cndmask_b32_e64 v41, 0, 32, vcc
	v_ldexp_f32 v40, v40, v41
	v_log_f32_e32 v40, v40
	s_nop 0
	v_mul_f32_e32 v41, 0x3f317217, v40
	v_fma_f32 v41, v40, s92, -v41
	v_fmac_f32_e32 v41, 0x3377d1cf, v40
	v_fmac_f32_e32 v41, 0x3f317217, v40
	v_cmp_lt_f32_e64 s[40:41], |v40|, s93
	s_nop 1
	v_cndmask_b32_e64 v40, v40, v41, s[40:41]
	v_cndmask_b32_e32 v41, 0, v231, vcc
	v_sub_f32_e32 v61, v40, v41
	v_pk_add_f32 v[40:41], v[58:59], v[60:61] neg_lo:[0,1] neg_hi:[0,1]
	ds_read_b128 v[54:57], v52 offset:1536
	ds_read_b128 v[58:61], v52 offset:1552
	v_pk_mul_f32 v[40:41], v[40:41], s[78:79] op_sel_hi:[1,0]
	s_waitcnt lgkmcnt(1)
	v_mov_b32_e32 v42, v54
	s_waitcnt lgkmcnt(0)
	v_mov_b32_e32 v43, v58
	v_mov_b32_e32 v58, v55
	v_pk_mul_f32 v[54:55], v[24:25], v[58:59]
	s_nop 0
	v_pk_fma_f32 v[42:43], v[20:21], v[42:43], v[54:55]
	v_mov_b32_e32 v54, v56
	v_mov_b32_e32 v55, v60
	v_pk_fma_f32 v[42:43], v[18:19], v[54:55], v[42:43]
	v_mov_b32_e32 v60, v57
	v_pk_fma_f32 v[42:43], v[14:15], v[60:61], v[42:43]
	ds_read_b128 v[54:57], v52 offset:1568
	ds_read_b128 v[58:61], v52 offset:1584
	v_add_f32_e32 v42, v51, v42
	v_add_f32_e32 v53, v42, v43
	s_waitcnt lgkmcnt(1)
	v_mov_b32_e32 v42, v54
	s_waitcnt lgkmcnt(0)
	v_mov_b32_e32 v43, v58
	v_mov_b32_e32 v58, v55
	v_pk_mul_f32 v[54:55], v[28:29], v[58:59]
	s_nop 0
	v_pk_fma_f32 v[42:43], v[26:27], v[42:43], v[54:55]
	v_mov_b32_e32 v54, v56
	v_mov_b32_e32 v55, v60
	v_pk_fma_f32 v[42:43], v[22:23], v[54:55], v[42:43]
	v_mov_b32_e32 v60, v57
	v_pk_fma_f32 v[42:43], v[16:17], v[60:61], v[42:43]
	ds_read_b128 v[54:57], v52 offset:1664
	ds_read_b128 v[58:61], v52 offset:1680
	v_add_f32_e32 v42, v53, v42
	v_add_f32_e32 v43, v42, v43
	v_min_f32_e32 v42, 0, v43
	v_mul_f32_e64 v43, |v43|, s33
	v_exp_f32_e32 v43, v43
	s_waitcnt lgkmcnt(0)
	v_mov_b32_e32 v65, v58
	v_mov_b32_e32 v58, v55
	v_mov_b32_e32 v64, v54
	v_add_f32_e32 v43, 1.0, v43
	v_cmp_gt_f32_e32 vcc, s80, v43
	v_pk_mul_f32 v[54:55], v[24:25], v[58:59]
	v_mov_b32_e32 v58, v56
	v_cndmask_b32_e64 v53, 0, 32, vcc
	v_ldexp_f32 v43, v43, v53
	v_log_f32_e32 v43, v43
	v_pk_fma_f32 v[54:55], v[20:21], v[64:65], v[54:55]
	v_mov_b32_e32 v59, v60
	v_pk_fma_f32 v[54:55], v[18:19], v[58:59], v[54:55]
	v_mul_f32_e32 v53, 0x3f317217, v43
	v_fma_f32 v53, v43, s92, -v53
	v_fmac_f32_e32 v53, 0x3377d1cf, v43
	v_fmac_f32_e32 v53, 0x3f317217, v43
	v_cmp_lt_f32_e64 s[40:41], |v43|, s93
	v_mov_b32_e32 v60, v57
	v_pk_fma_f32 v[54:55], v[14:15], v[60:61], v[54:55]
	v_cndmask_b32_e64 v43, v43, v53, s[40:41]
	v_cndmask_b32_e32 v53, 0, v231, vcc
	v_sub_f32_e32 v62, v43, v53
	v_add_f32_e32 v43, v51, v54
	v_add_f32_e32 v43, v43, v55
	ds_read_b128 v[54:57], v52 offset:1696
	ds_read_b128 v[58:61], v52 offset:1712
	s_waitcnt lgkmcnt(1)
	v_mov_b32_e32 v64, v54
	s_waitcnt lgkmcnt(0)
	v_mov_b32_e32 v65, v58
	v_mov_b32_e32 v58, v55
	v_pk_mul_f32 v[54:55], v[28:29], v[58:59]
	v_mov_b32_e32 v58, v56
	v_pk_fma_f32 v[54:55], v[26:27], v[64:65], v[54:55]
	v_mov_b32_e32 v59, v60
	v_pk_fma_f32 v[54:55], v[22:23], v[58:59], v[54:55]
	v_mov_b32_e32 v60, v57
	v_pk_fma_f32 v[54:55], v[16:17], v[60:61], v[54:55]
	s_nop 0
	v_add_f32_e32 v43, v43, v54
	v_add_f32_e32 v53, v43, v55
	v_min_f32_e32 v43, 0, v53
	v_mul_f32_e64 v53, |v53|, s33
	v_exp_f32_e32 v53, v53
	s_nop 0
	v_add_f32_e32 v53, 1.0, v53
	v_cmp_gt_f32_e32 vcc, s80, v53
	s_nop 1
	v_cndmask_b32_e64 v54, 0, 32, vcc
	v_ldexp_f32 v53, v53, v54
	v_log_f32_e32 v53, v53
	s_nop 0
	v_mul_f32_e32 v54, 0x3f317217, v53
	v_fma_f32 v54, v53, s92, -v54
	v_fmac_f32_e32 v54, 0x3377d1cf, v53
	v_fmac_f32_e32 v54, 0x3f317217, v53
	v_cmp_lt_f32_e64 s[40:41], |v53|, s93
	s_nop 1
	v_cndmask_b32_e64 v53, v53, v54, s[40:41]
	v_cndmask_b32_e32 v54, 0, v231, vcc
	v_sub_f32_e32 v63, v53, v54
	ds_read_b128 v[54:57], v52 offset:1792
	ds_read_b128 v[58:61], v52 offset:1808
	v_pk_add_f32 v[42:43], v[42:43], v[62:63] neg_lo:[0,1] neg_hi:[0,1]
	s_waitcnt lgkmcnt(1)
; #define LAS __attribute__((address_space(3)))
; __device__ __forceinline__ void gla_gates(CP P, const bf16_t* PQ, int m0, int h, LAS unsigned char* lds) {
;     ...
;     for (int i = 0; i < 16; ++i) { const int t = tq * 16 + i; float z = b;
; #pragma unroll
;         for (int r4 = 0; r4 < 4; ++r4) { const f32x4 g4 = *(const LAS f32x4*)(gl + t * 32 + dir * 16 + r4 * 4);
;             z += g4[0] * w[r4 * 4] + g4[1] * w[r4 * 4 + 1] + g4[2] * w[r4 * 4 + 2] + g4[3] * w[r4 * 4 + 3]; }
;         c[i] = (fminf(z, 0.f) - __logf(1.0f + __expf(-fabsf(z)))) * (1.0f / 16.0f); }
;     if (dir == 0) {
; #pragma unroll
;         for (int i = 1; i < 16; ++i) c[i] += c[i - 1];
;         tot[(dir * 4 + tq) * 64 + d] = c[15]; }
;     else {
; #pragma unroll
;         for (int i = 14; i >= 0; --i) c[i] += c[i + 1];
;         tot[(dir * 4 + tq) * 64 + d] = c[0]; }
	v_mov_b32_e32 v62, v54
	s_waitcnt lgkmcnt(0)
	v_mov_b32_e32 v63, v58
	v_mov_b32_e32 v58, v55
	v_pk_mul_f32 v[54:55], v[24:25], v[58:59]
	v_mov_b32_e32 v58, v56
	v_pk_fma_f32 v[54:55], v[20:21], v[62:63], v[54:55]
	v_mov_b32_e32 v59, v60
	v_pk_fma_f32 v[54:55], v[18:19], v[58:59], v[54:55]
	v_mov_b32_e32 v60, v57
	v_pk_fma_f32 v[54:55], v[14:15], v[60:61], v[54:55]
	v_pk_mul_f32 v[42:43], v[42:43], s[78:79] op_sel_hi:[1,0]
	v_add_f32_e32 v53, v51, v54
	v_add_f32_e32 v53, v53, v55
	ds_read_b128 v[54:57], v52 offset:1824
	ds_read_b128 v[58:61], v52 offset:1840
	s_waitcnt lgkmcnt(1)
	v_mov_b32_e32 v62, v54
	s_waitcnt lgkmcnt(0)
	v_mov_b32_e32 v63, v58
	v_mov_b32_e32 v58, v55
	v_pk_mul_f32 v[54:55], v[28:29], v[58:59]
	v_mov_b32_e32 v58, v56
	v_pk_fma_f32 v[54:55], v[26:27], v[62:63], v[54:55]
	v_mov_b32_e32 v59, v60
	v_pk_fma_f32 v[54:55], v[22:23], v[58:59], v[54:55]
	v_mov_b32_e32 v60, v57
	v_pk_fma_f32 v[54:55], v[16:17], v[60:61], v[54:55]
	s_nop 0
	v_add_f32_e32 v53, v53, v54
	v_add_f32_e32 v53, v53, v55
	v_min_f32_e32 v62, 0, v53
	v_mul_f32_e64 v53, |v53|, s33
	v_exp_f32_e32 v53, v53
	s_nop 0
	v_add_f32_e32 v53, 1.0, v53
	v_cmp_gt_f32_e32 vcc, s80, v53
	s_nop 1
	v_cndmask_b32_e64 v54, 0, 32, vcc
	v_ldexp_f32 v53, v53, v54
	v_log_f32_e32 v53, v53
	s_nop 0
	v_mul_f32_e32 v54, 0x3f317217, v53
	v_fma_f32 v54, v53, s92, -v54
	v_fmac_f32_e32 v54, 0x3377d1cf, v53
	v_fmac_f32_e32 v54, 0x3f317217, v53
	v_cmp_lt_f32_e64 s[40:41], |v53|, s93
	s_nop 1
	v_cndmask_b32_e64 v53, v53, v54, s[40:41]
	v_cndmask_b32_e32 v54, 0, v231, vcc
	v_sub_f32_e32 v64, v53, v54
	ds_read_b128 v[54:57], v52 offset:1920
	ds_read_b128 v[58:61], v52 offset:1936
	s_waitcnt lgkmcnt(1)
	v_mov_b32_e32 v66, v54
	s_waitcnt lgkmcnt(0)
	v_mov_b32_e32 v67, v58
	v_mov_b32_e32 v58, v55
	v_pk_mul_f32 v[24:25], v[24:25], v[58:59]
	s_nop 0
	v_pk_fma_f32 v[20:21], v[20:21], v[66:67], v[24:25]
	v_mov_b32_e32 v24, v56
	v_mov_b32_e32 v25, v60
	v_pk_fma_f32 v[18:19], v[18:19], v[24:25], v[20:21]
	v_mov_b32_e32 v60, v57
	v_pk_fma_f32 v[14:15], v[14:15], v[60:61], v[18:19]
	ds_read_b128 v[18:21], v52 offset:1952
	ds_read_b128 v[52:55], v52 offset:1968
	v_add_f32_e32 v14, v51, v14
	v_add_f32_e32 v24, v14, v15
	s_waitcnt lgkmcnt(1)
	v_mov_b32_e32 v14, v18
	s_waitcnt lgkmcnt(0)
	v_mov_b32_e32 v15, v52
	v_mov_b32_e32 v52, v19
	v_pk_mul_f32 v[18:19], v[28:29], v[52:53]
	s_nop 0
	v_pk_fma_f32 v[14:15], v[26:27], v[14:15], v[18:19]
	v_mov_b32_e32 v18, v20
	v_mov_b32_e32 v19, v54
	v_pk_fma_f32 v[14:15], v[22:23], v[18:19], v[14:15]
	v_mov_b32_e32 v54, v21
	v_pk_fma_f32 v[14:15], v[16:17], v[54:55], v[14:15]
	v_lshlrev_b32_e32 v16, 2, v47
	v_add_f32_e32 v14, v24, v14
	v_add_f32_e32 v14, v14, v15
	v_min_f32_e32 v63, 0, v14
	v_mul_f32_e64 v14, |v14|, s33
	v_exp_f32_e32 v14, v14
	s_nop 0
	v_add_f32_e32 v14, 1.0, v14
	v_cmp_gt_f32_e32 vcc, s80, v14
	s_nop 1
	v_cndmask_b32_e64 v15, 0, 32, vcc
	v_ldexp_f32 v14, v14, v15
	v_log_f32_e32 v14, v14
	s_nop 0
	v_mul_f32_e32 v15, 0x3f317217, v14
	v_fma_f32 v15, v14, s92, -v15
	v_fmac_f32_e32 v15, 0x3377d1cf, v14
	v_fmac_f32_e32 v15, 0x3f317217, v14
	v_cmp_lt_f32_e64 s[40:41], |v14|, s93
	s_nop 1
	v_cndmask_b32_e64 v14, v14, v15, s[40:41]
	v_cndmask_b32_e32 v15, 0, v231, vcc
	v_sub_f32_e32 v65, v14, v15
	v_pk_add_f32 v[14:15], v[62:63], v[64:65] neg_lo:[0,1] neg_hi:[0,1]
	v_cmp_gt_u32_e32 vcc, s12, v49
	s_movk_i32 s12, 0xff
	v_pk_mul_f32 v[14:15], v[14:15], s[78:79] op_sel_hi:[1,0]
	v_cmp_lt_u32_e64 s[40:41], s12, v49
	s_and_saveexec_b64 s[12:13], s[40:41]
	s_xor_b64 s[20:21], exec, s[12:13]
	s_cbranch_execz .LBB0_207
	v_add_f32_e32 v18, v14, v15
	v_add_f32_e32 v19, v43, v18
	v_add_f32_e32 v20, v42, v19
	v_add_f32_e32 v21, v41, v20
	v_add_f32_e32 v22, v40, v21
	v_add_f32_e32 v23, v39, v22
	v_add_f32_e32 v24, v38, v23
	v_add_f32_e32 v25, v37, v24
	v_add_f32_e32 v26, v36, v25
	v_add_f32_e32 v27, v35, v26
	v_add_f32_e32 v28, v34, v27
	v_add_f32_e32 v29, v33, v28
	v_add_f32_e32 v51, v32, v29
	v_add_f32_e32 v52, v31, v51
	v_lshl_add_u32 v14, v50, 2, 0
	v_lshlrev_b32_e32 v17, 8, v48
	v_add_f32_e32 v30, v30, v52
	v_add3_u32 v14, v14, v17, v16
	ds_write_b32 v14, v30 offset:8192

; template <class Epi>
; __device__ __forceinline__ void gemm_phase(LAS unsigned char* lds, const Gemm g, const Epi& E) {
;     ...
;         const bool has_next = S.next(ui + 1, nxt);
;         const char* nA = has_next ? (const char*)g.A + (size_t)nxt.bz * g.strideA * 2 + (size_t)nxt.pm * tstepA : cA;
;         const char* nB = has_next ? (const char*)g.Bt + (size_t)nxt.bz * g.strideB * 2 + (size_t)nxt.pn * tstepB : cB;
;     ...
; #pragma unroll
;         for (int a = 0; a < 2; ++a)
; #pragma unroll
;             for (int b = 0; b < 2; ++b)
; #pragma unroll
;                 for (int m = 0; m < 4; ++m)
; #pragma unroll
;                     for (int n = 0; n < 2; ++n) acc[a][b][m][n] = (f32x4){0.f, 0.f, 0.f, 0.f};
;         cur = nxt; cA = nA; cB = nB; ++ui;
.LBB0_287:
	s_ashr_i32 s47, s46, 31
	s_lshl_b64 s[24:25], s[46:47], 20
	v_readlane_b32 s38, v255, 14
	s_add_u32 s56, s38, s24
	v_readlane_b32 s24, v255, 12
	s_addc_u32 s57, s24, s25
	s_and_b64 s[24:25], s[42:43], exec
	s_cselect_b32 s47, s57, s21
	s_cselect_b32 s66, s56, s20
	s_ashr_i32 s49, s48, 31
	s_lshl_b64 s[24:25], s[48:49], 20
	s_add_u32 s38, s64, s24
	s_addc_u32 s39, s65, s25
	s_and_b64 s[24:25], s[42:43], exec
	s_cselect_b32 s49, s39, s83
	s_cselect_b32 s69, s38, s82
	s_add_u32 s20, s20, 0x80080
	s_addc_u32 s21, s21, 0
	s_add_u32 s82, s82, 0x100
	v_mov_b64_e32 v[0:1], 0
	v_mov_b64_e32 v[2:3], 0
	v_mov_b64_e32 v[4:5], 0
	v_mov_b64_e32 v[6:7], 0
	v_mov_b64_e32 v[8:9], 0
	v_mov_b64_e32 v[10:11], 0
	v_mov_b64_e32 v[12:13], 0
	v_mov_b64_e32 v[14:15], 0
	v_mov_b64_e32 v[16:17], 0
	v_mov_b64_e32 v[18:19], 0
	v_mov_b64_e32 v[20:21], 0
	v_mov_b64_e32 v[22:23], 0
	v_mov_b64_e32 v[24:25], 0
	v_mov_b64_e32 v[26:27], 0
	v_mov_b64_e32 v[28:29], 0
	v_mov_b64_e32 v[30:31], 0
	v_mov_b64_e32 v[32:33], 0
	v_mov_b64_e32 v[34:35], 0
	v_mov_b64_e32 v[36:37], 0
	v_mov_b64_e32 v[38:39], 0
	v_mov_b64_e32 v[40:41], 0
	v_mov_b64_e32 v[42:43], 0
	v_mov_b64_e32 v[44:45], 0
	v_mov_b64_e32 v[46:47], 0
	v_mov_b64_e32 v[48:49], 0
	v_mov_b64_e32 v[50:51], 0
	v_mov_b64_e32 v[52:53], 0
	v_mov_b64_e32 v[54:55], 0
	v_mov_b64_e32 v[56:57], 0
	v_mov_b64_e32 v[58:59], 0
	v_mov_b64_e32 v[60:61], 0
	v_mov_b64_e32 v[62:63], 0
	v_mov_b64_e32 v[64:65], 0
	v_mov_b64_e32 v[66:67], 0
	v_mov_b64_e32 v[68:69], 0
	v_mov_b64_e32 v[70:71], 0
	v_mov_b64_e32 v[72:73], 0
	v_mov_b64_e32 v[74:75], 0
	v_mov_b64_e32 v[76:77], 0
	v_mov_b64_e32 v[78:79], 0
	v_mov_b64_e32 v[80:81], 0
	v_mov_b64_e32 v[82:83], 0
	v_mov_b64_e32 v[84:85], 0
	v_mov_b64_e32 v[86:87], 0
	v_mov_b64_e32 v[88:89], 0
	v_mov_b64_e32 v[90:91], 0
	v_mov_b64_e32 v[92:93], 0
	v_mov_b64_e32 v[94:95], 0
	v_mov_b64_e32 v[96:97], 0
	v_mov_b64_e32 v[98:99], 0
	v_mov_b64_e32 v[100:101], 0
	v_mov_b64_e32 v[102:103], 0
	v_mov_b64_e32 v[104:105], 0
	v_mov_b64_e32 v[106:107], 0
	v_mov_b64_e32 v[108:109], 0
	v_mov_b64_e32 v[110:111], 0
	v_mov_b64_e32 v[112:113], 0
	v_mov_b64_e32 v[114:115], 0
	v_mov_b64_e32 v[116:117], 0
	v_mov_b64_e32 v[118:119], 0
	v_mov_b64_e32 v[120:121], 0
	v_mov_b64_e32 v[122:123], 0
	v_mov_b64_e32 v[124:125], 0
	v_mov_b64_e32 v[126:127], 0
	v_mov_b32_e32 v229, 0xbb00200b
	v_mov_b32_e32 v190, 0xbb80402b
	s_addc_u32 s83, s83, 0
	s_mov_b32 s84, -2
	s_waitcnt lgkmcnt(0)
